# ADIFF fast loop: the pre-barrier scalar work (slot delta, K base, DMA addresses) spread over the gaps of PV pairs 4-6; only wait + barrier remain at the end of pair 7
# baseline (speedup 1.0000x reference)
; #define LAS __attribute__((address_space(3)))
; __device__ __forceinline__ void diff_attn_phase(const Params& p, LAS unsigned char* lds) {
;     ...
;         for (int ch = 0; ch < NCH; ++ch) {
;             if (ch + 1 < NCH) asm volatile("s_waitcnt vmcnt(4)" ::: "memory"); else asm volatile("s_waitcnt vmcnt(0)" ::: "memory");
;             __builtin_amdgcn_s_barrier(); asm volatile("" ::: "memory");
;             if (ch + 2 < NCH) issue(ch + 2, s_nn);
;             const LAS unsigned char* Ksb = lds + s_cur * STG; const LAS unsigned char* Vsb = Ksb + 16384;
;             s_nn = s_cur; s_cur = (s_cur == 2) ? 0 : s_cur + 1;
; #pragma clang loop unroll(disable)
;             for (int u = 0; u < 2; ++u) {
;                 const LAS unsigned char* Ku = Ksb + u * 8192; const LAS unsigned char* Vu = Vsb + u * 8192;
;                 int kxl = kx, vb0l = vb0, vb1l = vb1; asm volatile("" : "+v"(kxl), "+v"(vb0l), "+v"(vb1l));
;                 bf16x8 kf[4];
; #pragma unroll
;                 for (int ks = 0; ks < 4; ++ks) kf[ks] = *(const LAS bf16x8*)(Ku + kbase + (kxl ^ (32 * ks)));
;                 bf16x8 P[2][2];
; #pragma unroll
;                 for (int r = 0; r < 2; ++r) {
;                     f32x16 S;
; #pragma unroll
;                     for (int i = 0; i < 16; ++i) S[i] = 0.f;
; #pragma unroll
;                     for (int ks = 0; ks < 4; ++ks) S = __builtin_amdgcn_mfma_f32_32x32x16_bf16(kf[ks], qf[r][ks], S, 0, 0, 0);
;                     S = __builtin_amdgcn_mfma_f32_32x32x16_bf16(kone, qm[r], S, 0, 0, 0);
; #pragma unroll
;                     for (int i = 0; i < 16; ++i) S[i] = __builtin_amdgcn_exp2f(S[i]);
;                     l[r] += sum16(S);
;                     P[r][0] = pack8(S, 0); P[r][1] = pack8(S, 8);
;                 }
; #pragma unroll
;                 for (int t = 0; t < 4; ++t) {
;                     const LAS unsigned char* a0 = Vu + (vb0l ^ (64 * t)); const LAS unsigned char* a1 = Vu + (vb1l ^ (64 * t));
;                     const bf16x8 v0 = tr_pair(a0, a1), v1 = tr_pair(a0 + 4096, a1 + 4096);
;                     O[0][t] = __builtin_amdgcn_mfma_f32_32x32x16_bf16(v0, P[0][0], O[0][t], 0, 0, 0);
;                     O[1][t] = __builtin_amdgcn_mfma_f32_32x32x16_bf16(v0, P[1][0], O[1][t], 0, 0, 0);
;                     O[0][t] = __builtin_amdgcn_mfma_f32_32x32x16_bf16(v1, P[0][1], O[0][t], 0, 0, 0);
.Lfb_loopF:
	s_waitcnt lgkmcnt(3)
	v_mfma_f32_32x32x16_bf16 v[146:161], v[198:201], v[166:169], 0
	v_exp_f32_e32 v138, v138
	v_exp_f32_e32 v139, v139
	v_exp_f32_e32 v140, v140
	v_exp_f32_e32 v141, v141
	s_waitcnt lgkmcnt(2)
	v_mfma_f32_32x32x16_bf16 v[146:161], v[202:205], v[170:173], v[146:161]
	v_add_f32_e32 v212, v212, v138
	v_add_f32_e32 v212, v212, v139
	v_add_f32_e32 v212, v212, v140
	v_add_f32_e32 v212, v212, v141
	v_exp_f32_e32 v142, v142
	v_exp_f32_e32 v143, v143
	s_waitcnt lgkmcnt(1)
	v_mfma_f32_32x32x16_bf16 v[146:161], v[208:211], v[174:177], v[146:161]
	v_exp_f32_e32 v144, v144
	v_exp_f32_e32 v145, v145
	v_add_f32_e32 v212, v212, v142
	v_add_f32_e32 v212, v212, v143
	s_waitcnt lgkmcnt(0)
	v_mfma_f32_32x32x16_bf16 v[146:161], v[230:233], v[178:181], v[146:161]
	v_add_f32_e32 v212, v212, v144
	v_add_f32_e32 v212, v212, v145
	v_cvt_pk_bf16_f32 v226, v138, v139
	v_cvt_pk_bf16_f32 v227, v140, v141
	v_cvt_pk_bf16_f32 v228, v142, v143
	v_cvt_pk_bf16_f32 v229, v144, v145
	v_mfma_f32_32x32x16_bf16 v[130:145], v[198:201], v[182:185], 0
	ds_read_b64_tr_b16 v[198:199], v234 offset:16384
	ds_read_b64_tr_b16 v[200:201], v235 offset:16384
	v_mfma_f32_32x32x16_bf16 v[130:145], v[202:205], v[186:189], v[130:145]
	ds_read_b64_tr_b16 v[202:203], v237 offset:16384
	ds_read_b64_tr_b16 v[204:205], v236 offset:16384
	v_exp_f32_e32 v146, v146
	v_exp_f32_e32 v147, v147
	v_exp_f32_e32 v148, v148
	v_mfma_f32_32x32x16_bf16 v[130:145], v[208:211], v[190:193], v[130:145]
	ds_read_b64_tr_b16 v[208:209], v238 offset:16384
	ds_read_b64_tr_b16 v[210:211], v239 offset:16384
	v_exp_f32_e32 v149, v149
	v_add_f32_e32 v213, v213, v146
	v_add_f32_e32 v213, v213, v147
	v_add_f32_e32 v213, v213, v148
	v_mfma_f32_32x32x16_bf16 v[130:145], v[230:233], v[194:197], v[130:145]
	ds_read_b64_tr_b16 v[230:231], v250 offset:16384
	ds_read_b64_tr_b16 v[232:233], v251 offset:16384
	v_add_f32_e32 v213, v213, v149
	v_exp_f32_e32 v150, v150
	v_exp_f32_e32 v151, v151
	s_waitcnt lgkmcnt(6)
	v_mfma_f32_32x32x16_bf16 v[114:129], v[198:201], v[214:217], v[114:129]
	v_exp_f32_e32 v152, v152
	v_exp_f32_e32 v153, v153
	v_mfma_f32_32x32x16_bf16 v[50:65], v[198:201], v[218:221], v[50:65]
	ds_read_b64_tr_b16 v[198:199], v234 offset:20480
	ds_read_b64_tr_b16 v[200:201], v235 offset:20480
	v_add_f32_e32 v213, v213, v150
	v_add_f32_e32 v213, v213, v151
	v_add_f32_e32 v213, v213, v152
	v_add_f32_e32 v213, v213, v153
	s_add_i32 s2, s29, 1
	s_and_b32 s2, s2, 3
	s_mov_b32 s37, 0x8000
	s_cmp_eq_u32 s2, 0
	s_cselect_b32 s37, 0xfffe8000, s37
	v_add_u32_e32 v1, s37, v1
	s_waitcnt lgkmcnt(6)
	v_mfma_f32_32x32x16_bf16 v[98:113], v[202:205], v[214:217], v[98:113]
	v_exp_f32_e32 v154, v154
	v_exp_f32_e32 v155, v155
	v_mfma_f32_32x32x16_bf16 v[34:49], v[202:205], v[218:221], v[34:49]
	ds_read_b64_tr_b16 v[202:203], v237 offset:20480
	ds_read_b64_tr_b16 v[204:205], v236 offset:20480
	v_exp_f32_e32 v156, v156
	v_exp_f32_e32 v157, v157
	s_add_i32 s2, s29, 3
	s_lshl_b32 s10, s2, 6
	s_add_u32 s10, s26, s10
	s_addc_u32 s11, s27, 0
	s_lshl_b64 s[10:11], s[10:11], 13
	s_add_u32 s42, s25, s10
	s_waitcnt lgkmcnt(6)
	v_mfma_f32_32x32x16_bf16 v[82:97], v[208:211], v[214:217], v[82:97]
	v_add_f32_e32 v213, v213, v154
	v_add_f32_e32 v213, v213, v155
	v_add_f32_e32 v213, v213, v156
	v_add_f32_e32 v213, v213, v157
	v_mfma_f32_32x32x16_bf16 v[18:33], v[208:211], v[218:221], v[18:33]
	ds_read_b64_tr_b16 v[208:209], v238 offset:20480
	ds_read_b64_tr_b16 v[210:211], v239 offset:20480
	v_exp_f32_e32 v158, v158
	v_exp_f32_e32 v159, v159
	s_addc_u32 s43, s28, s11
	s_add_u32 s10, s22, s10
	s_addc_u32 s11, s23, s11
	s_and_b32 s2, s2, 3
	s_lshl_b32 s2, s2, 15
	s_add_i32 s2, s2, s34
	s_waitcnt lgkmcnt(6)
	v_mfma_f32_32x32x16_bf16 v[66:81], v[230:233], v[214:217], v[66:81]
	v_exp_f32_e32 v160, v160
	v_exp_f32_e32 v161, v161
	v_mfma_f32_32x32x16_bf16 v[2:17], v[230:233], v[218:221], v[2:17]
	ds_read_b64_tr_b16 v[230:231], v250 offset:20480
	ds_read_b64_tr_b16 v[232:233], v251 offset:20480
	v_add_f32_e32 v213, v213, v158
	v_add_f32_e32 v213, v213, v159
	v_add_f32_e32 v213, v213, v160
	v_add_f32_e32 v213, v213, v161
	s_cmpk_eq_u32 s29, 0x7f
	s_cbranch_scc1 .Lfb_last0F
	s_cmpk_eq_u32 s29, 0x7e
	s_cbranch_scc1 .Lfb_w0F
	s_waitcnt vmcnt(4)
